# nt stores for FFN hidden activations + one static s_setprio 1 for waves 4-7 during the attention phase
# baseline (speedup 1.0000x reference)
.LBB0_688:
	s_andn2_b64 vcc, exec, s[0:1]
	s_cbranch_vccnz .LBB0_825
	v_readfirstlane_b32 s98, v191
	s_bitcmp1_b32 s98, 8
	s_cbranch_scc0 .Lmyprio_skip
	s_setprio 1
.Lmyprio_skip:
	s_mov_b64 s[0:1], s[68:69]
	s_mov_b32 s4, s72
	s_and_b32 s2, s4, 7
	s_mov_b32 s5, s66
	s_cmp_lg_u32 s2, 0
	s_cbranch_scc0 .LBB0_758
	s_cmpk_gt_i32 s5, 0x3ff
	s_cbranch_scc1 .LBB0_759

.LBB0_757:
	s_setprio 0
	v_readlane_b32 s68, v254, 7
	v_readlane_b32 s74, v254, 11
	v_readlane_b32 s44, v255, 15
	v_readlane_b32 s82, v255, 17
	v_readlane_b32 s92, v255, 19
	v_readlane_b32 s66, v254, 6
	v_readlane_b32 s69, v254, 8
	v_readlane_b32 s72, v254, 9
	v_readlane_b32 s75, v254, 12
	v_readlane_b32 s8, v255, 10
	v_readlane_b32 s45, v255, 16
	v_readlane_b32 s83, v255, 18
	v_readlane_b32 s93, v255, 20
	s_movk_i32 s9, 0x7ff
	s_movk_i32 s19, 0x300
	v_readlane_b32 s50, v255, 22
	v_readlane_b32 s73, v254, 10
	v_readlane_b32 s51, v255, 23
	s_or_b32 s4, s81, 5
	s_cmp_ge_i32 s4, s75
	s_cbranch_scc1 .LBB0_825
	s_branch .LBB0_760
